# sgu unit: U and b_sp loads of the gating epilogue issued once before the MFMA step into free registers instead of a load-wait-store ladder
# speedup vs baseline: 1.0040x; 1.0029x over previous
; #define LAS __attribute__((address_space(3)))
; __device__ __forceinline__ unsigned pk2(float lo, float hi) { return cvt_pk_bf16(lo, hi); }
; __device__ __forceinline__ void unit(const Frame& F, int c, int g, const bf16x8 (&af)[4][4]) {
;     ...
;     for (int cc = 0; cc < 4; ++cc) {
;         const int chunk = w * 4 + cc, r0 = 2 * lane;
;         const u32x4 x0 = *(const u32x4*)(F.V + (size_t)(tok0 + r0) * EA + ch0 + chunk * 8), x1 = *(const u32x4*)(F.V + (size_t)(tok0 + r0 + 1) * EA + ch0 + chunk * 8);
;         const f32x2 s0 = ST[r0], s1 = ST[r0 + 1];
;         const f32x4 ga = *(const f32x4*)(F.lnv_g + ch0 + chunk * 8), gb = *(const f32x4*)(F.lnv_g + ch0 + chunk * 8 + 4);
;         const f32x4 ba = *(const f32x4*)(F.lnv_b + ch0 + chunk * 8), bb = *(const f32x4*)(F.lnv_b + ch0 + chunk * 8 + 4);
;         const float gn[8] = {ga[0], ga[1], ga[2], ga[3], gb[0], gb[1], gb[2], gb[3]}, bs[8] = {ba[0], ba[1], ba[2], ba[3], bb[0], bb[1], bb[2], bb[3]};
;         const unsigned xa[4] = {x0.x, x0.y, x0.z, x0.w}, xb[4] = {x1.x, x1.y, x1.z, x1.w};
; #pragma unroll
;         for (int i = 0; i < 8; ++i) {
;             const float v0 = (i & 1) ? bfhi(xa[i >> 1]) : bflo(xa[i >> 1]), v1 = (i & 1) ? bfhi(xb[i >> 1]) : bflo(xb[i >> 1]);
;             const float n0 = (v0 - s0.x) * s0.y * gn[i] + bs[i], n1 = (v1 - s1.x) * s1.y * gn[i] + bs[i];
;             { const int chl = chunk * 8 + i;
;               const int slot = (chl & ~31) + 16 * ((chl >> 2) & 1) + 4 * ((chl >> 3) & 3) + (chl & 3);
;               *(LAS unsigned*)(lds + VT_OFF + slot * VT_STRIDE + lane * 4) = pk2(n0, n1); }
;         }
;     }
.LBB0_305:
	s_or_b64 exec, exec, s[62:63]
	v_and_b32_e32 v70, 63, v110
	v_lshl_or_b32 v64, v70, 1, s60
	v_ashrrev_i32_e32 v65, 31, v64
	s_and_b32 s61, s72, 7
	v_lshlrev_b64 v[66:67], 12, v[64:65]
	v_lshl_add_u64 v[66:67], s[76:77], 0, v[66:67]
	s_lshl_b32 s6, s61, 9
	s_lshl_b32 s50, s61, 10
	v_or_b32_e32 v64, 1, v64
	v_lshl_add_u64 v[66:67], v[66:67], 0, s[6:7]
	v_mov_b32_e32 v111, s50
	v_ashrrev_i32_e32 v65, 31, v64
	s_waitcnt lgkmcnt(0)
	s_barrier
	v_lshl_add_u64 v[68:69], v[66:67], 0, s[58:59]
	global_load_dwordx4 v[104:107], v111, s[8:9]
	global_load_dwordx4 v[116:119], v111, s[22:23]
	global_load_dwordx4 v[120:123], v[68:69], off
	v_lshlrev_b64 v[64:65], 12, v[64:65]
	v_lshl_add_u64 v[64:65], s[76:77], 0, v[64:65]
	v_lshl_add_u64 v[64:65], v[64:65], 0, s[6:7]
	v_lshl_add_u64 v[76:77], v[64:65], 0, s[58:59]
	global_load_dwordx4 v[124:127], v[76:77], off
	global_load_dwordx4 v[128:131], v111, s[8:9] offset:16
	global_load_dwordx4 v[132:135], v111, s[22:23] offset:16
	global_load_dwordx4 v[80:83], v[68:69], off offset:16
	global_load_dwordx4 v[84:87], v[76:77], off offset:16
	global_load_dwordx4 v[88:91], v111, s[8:9] offset:48
	global_load_dwordx4 v[96:99], v111, s[8:9] offset:32
	global_load_dwordx4 v[92:95], v111, s[22:23] offset:48
	global_load_dwordx4 v[100:103], v111, s[22:23] offset:32
	v_lshl_add_u32 v64, v70, 4, 0
	v_add_u32_e32 v152, 0x11000, v64
	ds_read_b128 v[136:139], v152
	v_lshl_add_u32 v115, v70, 2, 0
	v_add_u32_e32 v153, s1, v115
	v_add_u32_e32 v154, s3, v115
	v_add_u32_e32 v155, 0x1000, v153
	s_waitcnt lgkmcnt(0)
	v_mov_b32_e32 v112, v136
	v_mov_b32_e32 v113, v138
	v_mov_b32_e32 v138, v137
	global_load_dwordx4 v[64:67], v[68:69], off offset:48
	global_load_dwordx4 v[72:75], v[68:69], off offset:32
	s_nop 0
	global_load_dwordx4 v[68:71], v[76:77], off offset:48
	s_nop 0
	global_load_dwordx4 v[76:79], v[76:77], off offset:32
	s_add_i32 s72, s72, s34
	s_add_i32 s25, s25, s33
	s_add_i32 s35, s35, s64
	s_cmpk_lt_i32 s72, 0x600
	s_waitcnt vmcnt(15)
	v_mov_b32_e32 v108, v107
	s_waitcnt vmcnt(14)
	v_mov_b32_e32 v136, v119
	s_waitcnt vmcnt(13)
	v_lshlrev_b32_e32 v140, 16, v120
	v_and_b32_e32 v120, 0xffff0000, v120
	v_lshlrev_b32_e32 v142, 16, v121
	v_and_b32_e32 v144, 0xffff0000, v121
	s_waitcnt vmcnt(12)
	v_lshlrev_b32_e32 v141, 16, v124
	v_and_b32_e32 v121, 0xffff0000, v124
	v_lshlrev_b32_e32 v143, 16, v125
	v_lshlrev_b32_e32 v146, 16, v122
	v_and_b32_e32 v148, 0xffff0000, v122
	v_lshlrev_b32_e32 v150, 16, v123
	v_and_b32_e32 v145, 0xffff0000, v125
	v_lshlrev_b32_e32 v147, 16, v126
	v_and_b32_e32 v149, 0xffff0000, v126
	v_lshlrev_b32_e32 v151, 16, v127
	v_pk_add_f32 v[124:125], v[140:141], v[112:113] neg_lo:[0,1] neg_hi:[0,1]
	v_pk_add_f32 v[120:121], v[120:121], v[112:113] neg_lo:[0,1] neg_hi:[0,1]
	v_pk_add_f32 v[140:141], v[142:143], v[112:113] neg_lo:[0,1] neg_hi:[0,1]
	v_pk_add_f32 v[142:143], v[144:145], v[112:113] neg_lo:[0,1] neg_hi:[0,1]
	v_pk_add_f32 v[144:145], v[146:147], v[112:113] neg_lo:[0,1] neg_hi:[0,1]
	v_pk_add_f32 v[146:147], v[148:149], v[112:113] neg_lo:[0,1] neg_hi:[0,1]
	v_pk_add_f32 v[148:149], v[150:151], v[112:113] neg_lo:[0,1] neg_hi:[0,1]
	v_pk_mul_f32 v[124:125], v[138:139], v[124:125]
	v_pk_mul_f32 v[120:121], v[138:139], v[120:121]
	v_pk_mul_f32 v[140:141], v[138:139], v[140:141]
	v_pk_mul_f32 v[142:143], v[138:139], v[142:143]
	v_pk_mul_f32 v[144:145], v[138:139], v[144:145]
	v_pk_mul_f32 v[146:147], v[138:139], v[146:147]
	v_pk_mul_f32 v[148:149], v[138:139], v[148:149]
	v_pk_fma_f32 v[124:125], v[104:105], v[124:125], v[116:117] op_sel_hi:[0,1,0]
	v_pk_fma_f32 v[104:105], v[104:105], v[120:121], v[116:117] op_sel:[1,0,1]
	v_pk_fma_f32 v[106:107], v[106:107], v[140:141], v[118:119] op_sel_hi:[0,1,0]
	v_pk_fma_f32 v[116:117], v[108:109], v[142:143], v[136:137] op_sel_hi:[0,1,0]
	s_waitcnt vmcnt(10)
	v_pk_fma_f32 v[118:119], v[144:145], v[128:129], v[132:133] op_sel_hi:[1,0,0]
	v_pk_fma_f32 v[120:121], v[146:147], v[128:129], v[132:133] op_sel:[0,1,1]
	v_pk_fma_f32 v[128:129], v[148:149], v[130:131], v[134:135] op_sel_hi:[1,0,0]
	v_cvt_pk_bf16_f32 v108, v124, v125
	v_cvt_pk_bf16_f32 v104, v104, v105
	v_cvt_pk_bf16_f32 v105, v106, v107
	v_cvt_pk_bf16_f32 v106, v116, v117
	v_cvt_pk_bf16_f32 v107, v118, v119
	v_cvt_pk_bf16_f32 v116, v120, v121
	v_cvt_pk_bf16_f32 v117, v128, v129
	ds_write2_b32 v153, v108, v104 offset1:68
	ds_write2_b32 v153, v105, v106 offset0:136 offset1:204
	ds_write_b32 v154, v107
	ds_write2_b32 v155, v116, v117 offset0:132 offset1:200
	v_and_b32_e32 v105, 0xffff0000, v127
	v_and_b32_e32 v104, 0xffff0000, v123
	v_pk_add_f32 v[104:105], v[104:105], v[112:113] neg_lo:[0,1] neg_hi:[0,1]
	v_mov_b32_e32 v106, v131
	v_pk_mul_f32 v[104:105], v[138:139], v[104:105]
	v_mov_b32_e32 v108, v135
	v_pk_fma_f32 v[112:113], v[104:105], v[106:107], v[108:109] op_sel_hi:[1,0,0]
	global_load_dwordx4 v[104:107], v111, s[8:9] offset:64
	global_load_dwordx4 v[116:119], v111, s[22:23] offset:64
	v_cvt_pk_bf16_f32 v108, v112, v113
	ds_write_b32 v153, v108 offset:5168
	ds_read_b128 v[120:123], v152
	s_waitcnt vmcnt(11)
	v_lshlrev_b32_e32 v112, 16, v80
	s_waitcnt vmcnt(10)
	v_lshlrev_b32_e32 v113, 16, v84
	global_load_dwordx4 v[124:127], v111, s[8:9] offset:80
	global_load_dwordx4 v[128:131], v111, s[22:23] offset:80
	s_waitcnt lgkmcnt(0)
	v_mov_b32_e32 v132, v120
	v_mov_b32_e32 v133, v122
	v_pk_add_f32 v[112:113], v[112:113], v[132:133] neg_lo:[0,1] neg_hi:[0,1]
	v_mov_b32_e32 v122, v121
	v_pk_mul_f32 v[112:113], v[122:123], v[112:113]
	s_waitcnt vmcnt(8)
; #define LAS __attribute__((address_space(3)))
; __device__ __forceinline__ unsigned pk2(float lo, float hi) { return cvt_pk_bf16(lo, hi); }
; __device__ __forceinline__ void unit(const Frame& F, int c, int g, const bf16x8 (&af)[4][4]) {
;     ...
;         const int chunk = w * 4 + cc, r0 = 2 * lane;
;         const u32x4 x0 = *(const u32x4*)(F.V + (size_t)(tok0 + r0) * EA + ch0 + chunk * 8), x1 = *(const u32x4*)(F.V + (size_t)(tok0 + r0 + 1) * EA + ch0 + chunk * 8);
;         const f32x2 s0 = ST[r0], s1 = ST[r0 + 1];
;         const f32x4 ga = *(const f32x4*)(F.lnv_g + ch0 + chunk * 8), gb = *(const f32x4*)(F.lnv_g + ch0 + chunk * 8 + 4);
;         const f32x4 ba = *(const f32x4*)(F.lnv_b + ch0 + chunk * 8), bb = *(const f32x4*)(F.lnv_b + ch0 + chunk * 8 + 4);
;         const float gn[8] = {ga[0], ga[1], ga[2], ga[3], gb[0], gb[1], gb[2], gb[3]}, bs[8] = {ba[0], ba[1], ba[2], ba[3], bb[0], bb[1], bb[2], bb[3]};
;         const unsigned xa[4] = {x0.x, x0.y, x0.z, x0.w}, xb[4] = {x1.x, x1.y, x1.z, x1.w};
; #pragma unroll
;         for (int i = 0; i < 8; ++i) {
;             const float v0 = (i & 1) ? bfhi(xa[i >> 1]) : bflo(xa[i >> 1]), v1 = (i & 1) ? bfhi(xb[i >> 1]) : bflo(xb[i >> 1]);
;             const float n0 = (v0 - s0.x) * s0.y * gn[i] + bs[i], n1 = (v1 - s1.x) * s1.y * gn[i] + bs[i];
;             { const int chl = chunk * 8 + i;
;               const int slot = (chl & ~31) + 16 * ((chl >> 2) & 1) + 4 * ((chl >> 3) & 3) + (chl & 3);
;               *(LAS unsigned*)(lds + VT_OFF + slot * VT_STRIDE + lane * 4) = pk2(n0, n1); }
;         }
;     }
	v_pk_fma_f32 v[112:113], v[96:97], v[112:113], v[100:101] op_sel_hi:[0,1,0]
	v_cvt_pk_bf16_f32 v108, v112, v113
	v_and_b32_e32 v113, 0xffff0000, v84
	v_and_b32_e32 v112, 0xffff0000, v80
	v_pk_add_f32 v[112:113], v[112:113], v[132:133] neg_lo:[0,1] neg_hi:[0,1]
	v_and_b32_e32 v84, 0xffff0000, v81
	v_pk_mul_f32 v[112:113], v[122:123], v[112:113]
	s_nop 0
	v_pk_fma_f32 v[96:97], v[96:97], v[112:113], v[100:101] op_sel:[1,0,1]
	v_add_u32_e32 v100, 0x400, v153
	v_cvt_pk_bf16_f32 v80, v96, v97
	v_lshlrev_b32_e32 v96, 16, v81
	v_lshlrev_b32_e32 v97, 16, v85
	v_pk_add_f32 v[96:97], v[96:97], v[132:133] neg_lo:[0,1] neg_hi:[0,1]
	v_and_b32_e32 v85, 0xffff0000, v85
	v_pk_mul_f32 v[96:97], v[122:123], v[96:97]
	ds_write2_b32 v100, v108, v80 offset0:16 offset1:84
	v_pk_fma_f32 v[96:97], v[98:99], v[96:97], v[102:103] op_sel_hi:[0,1,0]
	v_pk_add_f32 v[80:81], v[84:85], v[132:133] neg_lo:[0,1] neg_hi:[0,1]
	v_cvt_pk_bf16_f32 v97, v96, v97
	v_pk_mul_f32 v[80:81], v[122:123], v[80:81]
	v_mov_b32_e32 v84, v99
	v_mov_b32_e32 v96, v103
	v_pk_fma_f32 v[80:81], v[84:85], v[80:81], v[96:97] op_sel_hi:[0,1,0]
	v_cvt_pk_bf16_f32 v80, v80, v81
	ds_write2_b32 v100, v97, v80 offset0:152 offset1:220
	v_lshlrev_b32_e32 v80, 16, v82
	v_lshlrev_b32_e32 v81, 16, v86
	v_pk_add_f32 v[80:81], v[80:81], v[132:133] neg_lo:[0,1] neg_hi:[0,1]
	s_waitcnt vmcnt(6)
	v_lshlrev_b32_e32 v100, 16, v72
	v_pk_mul_f32 v[80:81], v[122:123], v[80:81]
	s_waitcnt vmcnt(4)
	v_lshlrev_b32_e32 v101, 16, v76
	v_pk_fma_f32 v[80:81], v[80:81], v[88:89], v[92:93] op_sel_hi:[1,0,0]
	v_and_b32_e32 v108, 15, v110
	v_cvt_pk_bf16_f32 v84, v80, v81
	v_and_b32_e32 v81, 0xffff0000, v86
	v_and_b32_e32 v80, 0xffff0000, v82
	v_pk_add_f32 v[80:81], v[80:81], v[132:133] neg_lo:[0,1] neg_hi:[0,1]
	v_mov_b32_e32 v82, v91
	v_pk_mul_f32 v[80:81], v[122:123], v[80:81]
	v_or_b32_e32 v112, s0, v108
	v_pk_fma_f32 v[80:81], v[80:81], v[88:89], v[92:93] op_sel:[0,1,1]
	s_nop 0
	v_cvt_pk_bf16_f32 v80, v80, v81
	v_add_u32_e32 v81, 0x1400, v153
	ds_write2_b32 v81, v84, v80 offset0:80 offset1:148
	v_lshlrev_b32_e32 v80, 16, v83
	v_lshlrev_b32_e32 v81, 16, v87
	v_pk_add_f32 v[80:81], v[80:81], v[132:133] neg_lo:[0,1] neg_hi:[0,1]
	v_mov_b32_e32 v84, v95
	v_pk_mul_f32 v[80:81], v[122:123], v[80:81]
	s_nop 0
	v_pk_fma_f32 v[80:81], v[80:81], v[90:91], v[94:95] op_sel_hi:[1,0,0]
	v_add_u32_e32 v90, 0x1600, v153
	v_cvt_pk_bf16_f32 v88, v80, v81
	v_and_b32_e32 v81, 0xffff0000, v87
	v_and_b32_e32 v80, 0xffff0000, v83
	v_pk_add_f32 v[80:81], v[80:81], v[132:133] neg_lo:[0,1] neg_hi:[0,1]
	s_nop 0
	v_pk_mul_f32 v[80:81], v[122:123], v[80:81]
	s_nop 0
	v_pk_fma_f32 v[80:81], v[80:81], v[82:83], v[84:85] op_sel_hi:[1,0,0]
	s_nop 0
	v_cvt_pk_bf16_f32 v89, v80, v81
	global_load_dwordx4 v[80:83], v111, s[8:9] offset:96
	global_load_dwordx4 v[84:87], v111, s[22:23] offset:96
	ds_write2_b32 v90, v88, v89 offset0:88 offset1:156
	ds_read_b128 v[88:91], v152
	global_load_dwordx4 v[92:95], v111, s[8:9] offset:112
	global_load_dwordx4 v[96:99], v111, s[22:23] offset:112
	s_waitcnt lgkmcnt(0)
	v_mov_b32_e32 v102, v88
	v_mov_b32_e32 v103, v90
	v_pk_add_f32 v[100:101], v[100:101], v[102:103] neg_lo:[0,1] neg_hi:[0,1]
	v_mov_b32_e32 v90, v89
	v_pk_mul_f32 v[88:89], v[90:91], v[100:101]
	s_waitcnt vmcnt(6)
	v_pk_fma_f32 v[88:89], v[104:105], v[88:89], v[116:117] op_sel_hi:[0,1,0]
	v_cvt_pk_bf16_f32 v88, v88, v89
	v_add_u32_e32 v89, s10, v115
	ds_write_b32 v89, v88
	v_and_b32_e32 v89, 0xffff0000, v76
	v_and_b32_e32 v88, 0xffff0000, v72
	v_pk_add_f32 v[88:89], v[88:89], v[102:103] neg_lo:[0,1] neg_hi:[0,1]
	s_nop 0
	v_pk_mul_f32 v[88:89], v[90:91], v[88:89]
	s_nop 0
	v_pk_fma_f32 v[88:89], v[104:105], v[88:89], v[116:117] op_sel:[1,0,1]
	s_nop 0
	v_cvt_pk_bf16_f32 v72, v88, v89
	v_lshlrev_b32_e32 v88, 16, v73
	v_lshlrev_b32_e32 v89, 16, v77
	v_pk_add_f32 v[88:89], v[88:89], v[102:103] neg_lo:[0,1] neg_hi:[0,1]
	v_and_b32_e32 v77, 0xffff0000, v77
	v_pk_mul_f32 v[88:89], v[90:91], v[88:89]
	s_nop 0
	v_pk_fma_f32 v[88:89], v[106:107], v[88:89], v[118:119] op_sel_hi:[0,1,0]
	v_cvt_pk_bf16_f32 v76, v88, v89
	v_add_u32_e32 v88, 0x800, v153
	ds_write2_b32 v88, v72, v76 offset0:100 offset1:168
	v_and_b32_e32 v76, 0xffff0000, v73
	v_pk_add_f32 v[72:73], v[76:77], v[102:103] neg_lo:[0,1] neg_hi:[0,1]
	v_mov_b32_e32 v76, v107
	v_pk_mul_f32 v[72:73], v[90:91], v[72:73]
	v_mov_b32_e32 v88, v119
	v_pk_fma_f32 v[72:73], v[76:77], v[72:73], v[88:89] op_sel_hi:[0,1,0]
	v_cvt_pk_bf16_f32 v72, v72, v73
	ds_write_b32 v153, v72 offset:2992
	v_lshlrev_b32_e32 v72, 16, v74
	v_lshlrev_b32_e32 v73, 16, v78
	v_pk_add_f32 v[72:73], v[72:73], v[102:103] neg_lo:[0,1] neg_hi:[0,1]
	s_waitcnt vmcnt(4)
	v_mov_b32_e32 v76, v131
	v_pk_mul_f32 v[72:73], v[90:91], v[72:73]
	s_nop 0
	v_pk_fma_f32 v[72:73], v[72:73], v[124:125], v[128:129] op_sel_hi:[1,0,0]
	s_nop 0
	v_cvt_pk_bf16_f32 v72, v72, v73
	ds_write_b32 v154, v72 offset:2176
	v_and_b32_e32 v73, 0xffff0000, v78
	v_and_b32_e32 v72, 0xffff0000, v74
	v_pk_add_f32 v[72:73], v[72:73], v[102:103] neg_lo:[0,1] neg_hi:[0,1]
	s_nop 0
	v_pk_mul_f32 v[72:73], v[90:91], v[72:73]
	s_nop 0
	v_pk_fma_f32 v[72:73], v[72:73], v[124:125], v[128:129] op_sel:[0,1,1]
	s_nop 0
	v_cvt_pk_bf16_f32 v74, v72, v73
	v_lshlrev_b32_e32 v72, 16, v75
	v_lshlrev_b32_e32 v73, 16, v79
	v_pk_add_f32 v[72:73], v[72:73], v[102:103] neg_lo:[0,1] neg_hi:[0,1]
	s_nop 0
	v_pk_mul_f32 v[72:73], v[90:91], v[72:73]
	s_nop 0
	v_pk_fma_f32 v[72:73], v[72:73], v[126:127], v[130:131] op_sel_hi:[1,0,0]
	s_nop 0
	v_cvt_pk_bf16_f32 v72, v72, v73
	v_add_u32_e32 v73, 0x1800, v153
	ds_write2_b32 v73, v74, v72 offset0:164 offset1:232
	v_and_b32_e32 v73, 0xffff0000, v79
	v_and_b32_e32 v72, 0xffff0000, v75
	v_pk_add_f32 v[72:73], v[72:73], v[102:103] neg_lo:[0,1] neg_hi:[0,1]
	v_mov_b32_e32 v74, v127
	v_pk_mul_f32 v[72:73], v[90:91], v[72:73]
	s_nop 0
	v_pk_fma_f32 v[72:73], v[72:73], v[74:75], v[76:77] op_sel_hi:[1,0,0]
	v_lshlrev_b32_e32 v76, 16, v64
	v_cvt_pk_bf16_f32 v72, v72, v73
	ds_write_b32 v153, v72 offset:7344
	ds_read_b128 v[72:75], v152
	v_lshlrev_b32_e32 v77, 16, v68
	s_waitcnt lgkmcnt(0)
; #define LAS __attribute__((address_space(3)))
; __device__ __forceinline__ void unit(const Frame& F, int c, int g, const bf16x8 (&af)[4][4]) {
;     ...
;     __syncthreads();
;     f32x4 acc[4][4];
; #pragma unroll
;     for (int m = 0; m < 4; ++m)
; #pragma unroll
;         for (int n = 0; n < 4; ++n) acc[m][n] = (f32x4){0.f, 0.f, 0.f, 0.f};
; #pragma unroll
;     for (int ks = 0; ks < 4; ++ks) {
;         bf16x8 bfm[4];
; #pragma unroll
;         for (int n = 0; n < 4; ++n) bfm[n] = *(const LAS bf16x8*)(lds + VT_OFF + (wc * 64 + n * 16 + fr) * VT_STRIDE + ks * 64 + fq * 16);
; #pragma unroll
;         for (int m = 0; m < 4; ++m)
; #pragma unroll
;             for (int n = 0; n < 4; ++n) acc[m][n] = __builtin_amdgcn_mfma_f32_16x16x32_bf16(bfm[n], af[m][ks], acc[m][n], 0, 0, 0);
;     }
; #pragma unroll
;     for (int m = 0; m < 4; ++m) {
;         const int p = wr * 64 + m * 16 + fr; const float bsp = F.b_sp[g * 128 + p];
;         const size_t rowoff = (size_t)(tok0 + p) * EA + ch0 + wc * 64 + 8 * fq;
; #pragma unroll
;         for (int h2 = 0; h2 < 2; ++h2) {
;             const u32x4 uu = *(const u32x4*)(F.U + rowoff + h2 * 32);
;             const f32x4 s0 = acc[m][2 * h2] + bsp, s1 = acc[m][2 * h2 + 1] + bsp;
	v_mov_b32_e32 v78, v72
	v_mov_b32_e32 v79, v74
	v_pk_add_f32 v[76:77], v[76:77], v[78:79] neg_lo:[0,1] neg_hi:[0,1]
	v_mov_b32_e32 v74, v73
	v_pk_mul_f32 v[72:73], v[74:75], v[76:77]
	v_add_u32_e32 v77, 0xc00, v153
	s_waitcnt vmcnt(2)
	v_pk_fma_f32 v[72:73], v[80:81], v[72:73], v[84:85] op_sel_hi:[0,1,0]
	v_cvt_pk_bf16_f32 v76, v72, v73
	v_and_b32_e32 v73, 0xffff0000, v68
	v_and_b32_e32 v72, 0xffff0000, v64
	v_pk_add_f32 v[72:73], v[72:73], v[78:79] neg_lo:[0,1] neg_hi:[0,1]
	v_and_b32_e32 v68, 0xffff0000, v65
	v_pk_mul_f32 v[72:73], v[74:75], v[72:73]
	s_nop 0
	v_pk_fma_f32 v[72:73], v[80:81], v[72:73], v[84:85] op_sel:[1,0,1]
	s_nop 0
	v_cvt_pk_bf16_f32 v64, v72, v73
	v_lshlrev_b32_e32 v72, 16, v65
	v_lshlrev_b32_e32 v73, 16, v69
	v_pk_add_f32 v[72:73], v[72:73], v[78:79] neg_lo:[0,1] neg_hi:[0,1]
	v_and_b32_e32 v69, 0xffff0000, v69
	v_pk_mul_f32 v[72:73], v[74:75], v[72:73]
	ds_write2_b32 v77, v76, v64 offset0:48 offset1:116
	v_pk_fma_f32 v[72:73], v[82:83], v[72:73], v[86:87] op_sel_hi:[0,1,0]
	v_pk_add_f32 v[64:65], v[68:69], v[78:79] neg_lo:[0,1] neg_hi:[0,1]
	v_cvt_pk_bf16_f32 v73, v72, v73
	v_pk_mul_f32 v[64:65], v[74:75], v[64:65]
	v_mov_b32_e32 v68, v83
	v_mov_b32_e32 v72, v87
	v_pk_fma_f32 v[64:65], v[68:69], v[64:65], v[72:73] op_sel_hi:[0,1,0]
	v_cvt_pk_bf16_f32 v64, v64, v65
	ds_write2_b32 v77, v73, v64 offset0:184 offset1:252
	v_lshlrev_b32_e32 v64, 16, v66
	v_lshlrev_b32_e32 v65, 16, v70
	v_pk_add_f32 v[64:65], v[64:65], v[78:79] neg_lo:[0,1] neg_hi:[0,1]
	s_nop 0
	v_pk_mul_f32 v[64:65], v[74:75], v[64:65]
	s_waitcnt vmcnt(0)
	v_pk_fma_f32 v[64:65], v[64:65], v[92:93], v[96:97] op_sel_hi:[1,0,0]
	s_nop 0
	v_cvt_pk_bf16_f32 v68, v64, v65
	v_and_b32_e32 v65, 0xffff0000, v70
	v_and_b32_e32 v64, 0xffff0000, v66
	v_pk_add_f32 v[64:65], v[64:65], v[78:79] neg_lo:[0,1] neg_hi:[0,1]
	v_mov_b32_e32 v66, v95
	v_pk_mul_f32 v[64:65], v[74:75], v[64:65]
	s_nop 0
	v_pk_fma_f32 v[64:65], v[64:65], v[92:93], v[96:97] op_sel:[0,1,1]
	s_nop 0
	v_cvt_pk_bf16_f32 v64, v64, v65
	v_add_u32_e32 v65, 0x1c00, v153
	ds_write2_b32 v65, v68, v64 offset0:112 offset1:180
	v_lshlrev_b32_e32 v64, 16, v67
	v_lshlrev_b32_e32 v65, 16, v71
	v_pk_add_f32 v[64:65], v[64:65], v[78:79] neg_lo:[0,1] neg_hi:[0,1]
	v_mov_b32_e32 v68, v99
	v_pk_mul_f32 v[64:65], v[74:75], v[64:65]
	s_nop 0
	v_pk_fma_f32 v[64:65], v[64:65], v[94:95], v[98:99] op_sel_hi:[1,0,0]
	s_nop 0
	v_cvt_pk_bf16_f32 v69, v64, v65
	v_and_b32_e32 v65, 0xffff0000, v71
	v_and_b32_e32 v64, 0xffff0000, v67
	v_pk_add_f32 v[64:65], v[64:65], v[78:79] neg_lo:[0,1] neg_hi:[0,1]
	s_nop 0
	v_pk_mul_f32 v[64:65], v[74:75], v[64:65]
	s_nop 0
	v_pk_fma_f32 v[64:65], v[64:65], v[66:67], v[68:69] op_sel_hi:[1,0,0]
	s_nop 0
	v_cvt_pk_bf16_f32 v64, v64, v65
	v_add_u32_e32 v65, 0x1e00, v153
	ds_write2_b32 v65, v69, v64 offset0:120 offset1:188
	v_or_b32_e32 v64, s11, v108
	v_and_b32_e32 v65, 48, v110
	v_mul_u32_u24_e32 v64, 0x110, v64
	v_add3_u32 v111, 0, v65, v64
	s_waitcnt lgkmcnt(0)
	s_barrier
	v_lshrrev_b32_e32 v220, 1, v110
	v_and_or_b32 v221, v220, 24, s11
	v_lshl_or_b32 v221, v221, 1, s6
	v_add_u32_e32 v222, s60, v112
	v_lshl_or_b32 v224, v222, 12, v221
	v_add_u32_e32 v223, 16, v222
	v_lshl_or_b32 v225, v223, 12, v221
	v_add_u32_e32 v223, 32, v222
	v_lshl_or_b32 v226, v223, 12, v221
	v_add_u32_e32 v223, 48, v222
	v_lshl_or_b32 v227, v223, 12, v221
	v_lshl_add_u32 v228, s61, 7, v112
	v_lshlrev_b32_e32 v228, 2, v228
	global_load_dwordx4 v[184:187], v224, s[26:27]
	global_load_dwordx4 v[188:191], v224, s[26:27] offset:64
	global_load_dwordx4 v[192:195], v225, s[26:27]
	global_load_dwordx4 v[196:199], v225, s[26:27] offset:64
	global_load_dwordx4 v[200:203], v226, s[26:27]
	global_load_dwordx4 v[204:207], v226, s[26:27] offset:64
	global_load_dwordx4 v[208:211], v227, s[26:27]
	global_load_dwordx4 v[212:215], v227, s[26:27] offset:64
	global_load_dword v216, v228, s[20:21]
	global_load_dword v217, v228, s[20:21] offset:64
	global_load_dword v218, v228, s[20:21] offset:128
	global_load_dword v219, v228, s[20:21] offset:192
	ds_read_b128 v[64:67], v111
	ds_read_b128 v[68:71], v111 offset:64
	ds_read_b128 v[76:79], v111 offset:4352
	ds_read_b128 v[80:83], v111 offset:4416
	ds_read_b128 v[88:91], v111 offset:8704
	ds_read_b128 v[92:95], v111 offset:8768
	s_waitcnt lgkmcnt(5)
	v_mfma_f32_16x16x32_bf16 v[72:75], v[64:67], v[0:3], 0
	ds_read_b128 v[100:103], v111 offset:13056
	ds_read_b128 v[104:107], v111 offset:13120
	v_lshrrev_b32_e32 v110, 1, v110
	v_lshl_add_u32 v108, s61, 7, v112
	s_waitcnt lgkmcnt(3)
	v_mfma_f32_16x16x32_bf16 v[96:99], v[88:91], v[0:3], 0
	v_add_u32_e32 v112, s60, v112
	v_and_or_b32 v115, v110, 24, s11
	v_ashrrev_i32_e32 v113, 31, v112
	v_mfma_f32_16x16x32_bf16 v[128:131], v[88:91], v[16:19], 0
	v_lshl_or_b32 v115, v115, 1, s6
	v_mfma_f32_16x16x32_bf16 v[144:147], v[88:91], v[32:35], 0
	v_mfma_f32_16x16x32_bf16 v[88:91], v[88:91], v[48:51], 0
	v_mfma_f32_16x16x32_bf16 v[84:87], v[76:79], v[0:3], 0
	v_mfma_f32_16x16x32_bf16 v[120:123], v[64:67], v[16:19], 0
	v_mfma_f32_16x16x32_bf16 v[124:127], v[76:79], v[16:19], 0
	v_mfma_f32_16x16x32_bf16 v[136:139], v[64:67], v[32:35], 0
	v_mfma_f32_16x16x32_bf16 v[140:143], v[76:79], v[32:35], 0
	v_mfma_f32_16x16x32_bf16 v[64:67], v[64:67], v[48:51], 0
	v_mfma_f32_16x16x32_bf16 v[76:79], v[76:79], v[48:51], 0
	v_mfma_f32_16x16x32_bf16 v[72:75], v[68:71], v[4:7], v[72:75]
	s_waitcnt lgkmcnt(2)
; #define LAS __attribute__((address_space(3)))
; __device__ __forceinline__ unsigned pk2(float lo, float hi) { return cvt_pk_bf16(lo, hi); }
; __device__ __forceinline__ void unit(const Frame& F, int c, int g, const bf16x8 (&af)[4][4]) {
;     ...
;     for (int ks = 0; ks < 4; ++ks) {
;         bf16x8 bfm[4];
; #pragma unroll
;         for (int n = 0; n < 4; ++n) bfm[n] = *(const LAS bf16x8*)(lds + VT_OFF + (wc * 64 + n * 16 + fr) * VT_STRIDE + ks * 64 + fq * 16);
; #pragma unroll
;         for (int m = 0; m < 4; ++m)
; #pragma unroll
;             for (int n = 0; n < 4; ++n) acc[m][n] = __builtin_amdgcn_mfma_f32_16x16x32_bf16(bfm[n], af[m][ks], acc[m][n], 0, 0, 0);
;     }
; #pragma unroll
;     for (int m = 0; m < 4; ++m) {
;         const int p = wr * 64 + m * 16 + fr; const float bsp = F.b_sp[g * 128 + p];
;         const size_t rowoff = (size_t)(tok0 + p) * EA + ch0 + wc * 64 + 8 * fq;
; #pragma unroll
;         for (int h2 = 0; h2 < 2; ++h2) {
;             const u32x4 uu = *(const u32x4*)(F.U + rowoff + h2 * 32);
;             const f32x4 s0 = acc[m][2 * h2] + bsp, s1 = acc[m][2 * h2 + 1] + bsp;
;             u32x4 o;
;             o.x = pk2(bflo(uu.x) * s0[0], bfhi(uu.x) * s0[1]); o.y = pk2(bflo(uu.y) * s0[2], bfhi(uu.y) * s0[3]);
;             o.z = pk2(bflo(uu.z) * s1[0], bfhi(uu.z) * s1[1]); o.w = pk2(bflo(uu.w) * s1[2], bfhi(uu.w) * s1[3]);
;             *(u32x4*)(F.ABUF + rowoff + h2 * 32) = o;
;         }
	v_mfma_f32_16x16x32_bf16 v[96:99], v[92:95], v[4:7], v[96:99]
	v_mfma_f32_16x16x32_bf16 v[128:131], v[92:95], v[20:23], v[128:131]
	v_mfma_f32_16x16x32_bf16 v[144:147], v[92:95], v[36:39], v[144:147]
	v_mfma_f32_16x16x32_bf16 v[156:159], v[92:95], v[52:55], v[88:91]
	ds_read_b128 v[92:95], v111 offset:128
	s_nop 1
	ds_read_b128 v[88:91], v111 offset:192
	v_mfma_f32_16x16x32_bf16 v[84:87], v[80:83], v[4:7], v[84:87]
	v_mfma_f32_16x16x32_bf16 v[120:123], v[68:71], v[20:23], v[120:123]
	v_mfma_f32_16x16x32_bf16 v[124:127], v[80:83], v[20:23], v[124:127]
	v_mfma_f32_16x16x32_bf16 v[136:139], v[68:71], v[36:39], v[136:139]
	v_mfma_f32_16x16x32_bf16 v[140:143], v[80:83], v[36:39], v[140:143]
	v_mfma_f32_16x16x32_bf16 v[152:155], v[68:71], v[52:55], v[64:67]
	v_mfma_f32_16x16x32_bf16 v[76:79], v[80:83], v[52:55], v[76:79]
	s_waitcnt lgkmcnt(1)
	v_mfma_f32_16x16x32_bf16 v[164:167], v[92:95], v[8:11], v[72:75]
	s_nop 2
	ds_read_b128 v[72:75], v111 offset:4480
	ds_read_b128 v[80:83], v111 offset:4544
	ds_read_b128 v[172:175], v111 offset:8832
	ds_read_b128 v[68:71], v111 offset:8896
	ds_read_b128 v[180:183], v111 offset:13184
	ds_read_b128 v[64:67], v111 offset:13248
	s_waitcnt lgkmcnt(5)
	v_mfma_f32_16x16x32_bf16 v[168:171], v[72:75], v[8:11], v[84:87]
	v_lshl_add_u64 v[110:111], v[108:109], 2, s[20:21]
	s_nop 0
	v_mfma_f32_16x16x32_bf16 v[84:87], v[72:75], v[56:59], v[76:79]
	s_waitcnt lgkmcnt(3)
	v_mfma_f32_16x16x32_bf16 v[76:79], v[172:175], v[56:59], v[156:159]
	s_nop 2
	v_lshlrev_b64 v[156:157], 12, v[112:113]
	v_or_b32_e32 v156, v156, v115
	v_lshl_add_u64 v[158:159], s[26:27], 0, v[156:157]
	v_mfma_f32_16x16x32_bf16 v[120:123], v[92:95], v[24:27], v[120:123]
	v_mfma_f32_16x16x32_bf16 v[136:139], v[92:95], v[40:43], v[136:139]
	v_mfma_f32_16x16x32_bf16 v[92:95], v[92:95], v[56:59], v[152:155]
	s_nop 2
	s_nop 0
	v_mfma_f32_16x16x32_bf16 v[116:119], v[100:103], v[0:3], 0
	v_mfma_f32_16x16x32_bf16 v[132:135], v[100:103], v[16:19], 0
	v_mfma_f32_16x16x32_bf16 v[148:151], v[100:103], v[32:35], 0
	v_mfma_f32_16x16x32_bf16 v[100:103], v[100:103], v[48:51], 0
	v_mfma_f32_16x16x32_bf16 v[116:119], v[104:107], v[4:7], v[116:119]
	v_mfma_f32_16x16x32_bf16 v[132:135], v[104:107], v[20:23], v[132:135]
	v_mfma_f32_16x16x32_bf16 v[148:151], v[104:107], v[36:39], v[148:151]
	v_mfma_f32_16x16x32_bf16 v[160:163], v[104:107], v[52:55], v[100:103]
	v_mfma_f32_16x16x32_bf16 v[104:107], v[72:75], v[40:43], v[140:143]
	v_mfma_f32_16x16x32_bf16 v[140:143], v[88:91], v[12:15], v[164:167]
	v_mfma_f32_16x16x32_bf16 v[100:103], v[172:175], v[40:43], v[144:147]
	v_mfma_f32_16x16x32_bf16 v[144:147], v[80:83], v[12:15], v[168:171]
	s_waitcnt vmcnt(0)
	s_nop 1
	v_mov_b32_e32 v108, v216
	s_nop 4
	v_pk_add_f32 v[142:143], v[142:143], v[108:109] op_sel_hi:[1,0]
	v_mfma_f32_16x16x32_bf16 v[124:127], v[72:75], v[24:27], v[124:127]
	v_add_f32_e64 v140, v140, v108
	v_add_f32_e64 v141, v141, v108
	v_pk_add_f32 v[144:145], v[144:145], v[108:109] op_sel_hi:[1,0]
	v_pk_add_f32 v[146:147], v[146:147], v[108:109] op_sel_hi:[1,0]
	s_waitcnt lgkmcnt(1)
	v_mfma_f32_16x16x32_bf16 v[72:75], v[180:183], v[56:59], v[160:163]
	v_mfma_f32_16x16x32_bf16 v[176:179], v[172:175], v[8:11], v[96:99]
	s_nop 1
	v_mov_b32_e32 v152, v184
	v_mov_b32_e32 v153, v185
	v_mov_b32_e32 v154, v186
	v_mov_b32_e32 v155, v187
	s_nop 0
	v_lshlrev_b32_e32 v160, 16, v152
	v_and_b32_e32 v161, 0xffff0000, v152
	v_lshlrev_b32_e32 v152, 16, v153
	v_and_b32_e32 v153, 0xffff0000, v153
	v_pk_mul_f32 v[140:141], v[140:141], v[160:161]
	v_pk_mul_f32 v[142:143], v[142:143], v[152:153]
	v_cvt_pk_bf16_f32 v140, v140, v141
	v_cvt_pk_bf16_f32 v141, v142, v143
	v_lshlrev_b32_e32 v142, 16, v154
	v_and_b32_e32 v143, 0xffff0000, v154
	v_pk_mul_f32 v[142:143], v[144:145], v[142:143]
	v_lshlrev_b32_e32 v144, 16, v155
	v_and_b32_e32 v145, 0xffff0000, v155
	v_pk_mul_f32 v[144:145], v[146:147], v[144:145]
	v_cvt_pk_bf16_f32 v142, v142, v143
	v_cvt_pk_bf16_f32 v143, v144, v145
	v_lshl_add_u64 v[144:145], s[52:53], 0, v[156:157]
	global_store_dwordx4 v[144:145], v[140:143], off
	s_nop 0
	v_mfma_f32_16x16x32_bf16 v[116:119], v[180:183], v[8:11], v[116:119]
	v_mfma_f32_16x16x32_bf16 v[96:99], v[180:183], v[40:43], v[148:151]
	v_mfma_f32_16x16x32_bf16 v[148:151], v[68:71], v[12:15], v[176:179]
	s_waitcnt lgkmcnt(0)
; __device__ __forceinline__ unsigned pk2(float lo, float hi) { return cvt_pk_bf16(lo, hi); }
; __device__ __forceinline__ void unit(const Frame& F, int c, int g, const bf16x8 (&af)[4][4]) {
;     ...
;     for (int m = 0; m < 4; ++m) {
;         const int p = wr * 64 + m * 16 + fr; const float bsp = F.b_sp[g * 128 + p];
;         const size_t rowoff = (size_t)(tok0 + p) * EA + ch0 + wc * 64 + 8 * fq;
; #pragma unroll
;         for (int h2 = 0; h2 < 2; ++h2) {
;             const u32x4 uu = *(const u32x4*)(F.U + rowoff + h2 * 32);
;             const f32x4 s0 = acc[m][2 * h2] + bsp, s1 = acc[m][2 * h2 + 1] + bsp;
;             u32x4 o;
;             o.x = pk2(bflo(uu.x) * s0[0], bfhi(uu.x) * s0[1]); o.y = pk2(bflo(uu.y) * s0[2], bfhi(uu.y) * s0[3]);
;             o.z = pk2(bflo(uu.z) * s1[0], bfhi(uu.z) * s1[1]); o.w = pk2(bflo(uu.w) * s1[2], bfhi(uu.w) * s1[3]);
;             *(u32x4*)(F.ABUF + rowoff + h2 * 32) = o;
;         }
	v_mfma_f32_16x16x32_bf16 v[116:119], v[64:67], v[12:15], v[116:119]
	v_mfma_f32_16x16x32_bf16 v[120:123], v[88:91], v[28:31], v[120:123]
	s_nop 4
	v_add_f32_e64 v146, v150, v108
	v_add_f32_e64 v147, v151, v108
	v_pk_add_f32 v[148:149], v[148:149], v[108:109] op_sel_hi:[1,0]
	v_pk_add_f32 v[150:151], v[118:119], v[108:109] op_sel_hi:[1,0]
	v_pk_add_f32 v[118:119], v[116:117], v[108:109] op_sel_hi:[1,0]
	v_mfma_f32_16x16x32_bf16 v[124:127], v[80:83], v[28:31], v[124:127]
	s_nop 1
	v_mov_b32_e32 v140, v188
	v_mov_b32_e32 v141, v189
	v_mov_b32_e32 v142, v190
	v_mov_b32_e32 v143, v191
	v_lshlrev_b32_e32 v116, 16, v140
	v_and_b32_e32 v117, 0xffff0000, v140
	v_lshlrev_b32_e32 v140, 16, v141
	v_and_b32_e32 v141, 0xffff0000, v141
	v_pk_mul_f32 v[116:117], v[148:149], v[116:117]
	v_pk_mul_f32 v[140:141], v[146:147], v[140:141]
	v_cvt_pk_bf16_f32 v116, v116, v117
	v_cvt_pk_bf16_f32 v117, v140, v141
	v_lshlrev_b32_e32 v140, 16, v142
	v_and_b32_e32 v141, 0xffff0000, v142
	v_pk_mul_f32 v[118:119], v[118:119], v[140:141]
	v_lshlrev_b32_e32 v140, 16, v143
	v_and_b32_e32 v141, 0xffff0000, v143
	v_pk_mul_f32 v[140:141], v[150:151], v[140:141]
	v_cvt_pk_bf16_f32 v118, v118, v119
	v_cvt_pk_bf16_f32 v119, v140, v141
	global_store_dwordx4 v[144:145], v[116:119], off offset:64
	s_nop 0
	v_mfma_f32_16x16x32_bf16 v[128:131], v[172:175], v[24:27], v[128:131]
	v_add_u32_e32 v116, 16, v112
	v_ashrrev_i32_e32 v117, 31, v116
	v_lshlrev_b64 v[140:141], 12, v[116:117]
	v_or_b32_e32 v140, v140, v115
	v_lshl_add_u64 v[142:143], s[26:27], 0, v[140:141]
	s_nop 0
	v_mfma_f32_16x16x32_bf16 v[132:135], v[180:183], v[24:27], v[132:135]
	s_nop 1
	v_mov_b32_e32 v108, v217
	v_pk_add_f32 v[120:121], v[120:121], v[108:109] op_sel_hi:[1,0]
	v_pk_add_f32 v[122:123], v[122:123], v[108:109] op_sel_hi:[1,0]
	v_pk_add_f32 v[124:125], v[124:125], v[108:109] op_sel_hi:[1,0]
	v_pk_add_f32 v[126:127], v[126:127], v[108:109] op_sel_hi:[1,0]
	v_mfma_f32_16x16x32_bf16 v[128:131], v[68:71], v[28:31], v[128:131]
	s_nop 1
	v_mov_b32_e32 v116, v192
	v_mov_b32_e32 v117, v193
	v_mov_b32_e32 v118, v194
	v_mov_b32_e32 v119, v195
	v_lshlrev_b32_e32 v144, 16, v116
	v_and_b32_e32 v145, 0xffff0000, v116
	v_pk_mul_f32 v[120:121], v[120:121], v[144:145]
	v_mfma_f32_16x16x32_bf16 v[132:135], v[64:67], v[28:31], v[132:135]
	v_cvt_pk_bf16_f32 v116, v120, v121
	v_lshlrev_b32_e32 v120, 16, v117
	v_and_b32_e32 v121, 0xffff0000, v117
	v_pk_mul_f32 v[120:121], v[122:123], v[120:121]
	v_pk_add_f32 v[128:129], v[128:129], v[108:109] op_sel_hi:[1,0]
	v_cvt_pk_bf16_f32 v117, v120, v121
	v_lshlrev_b32_e32 v120, 16, v118
	v_and_b32_e32 v121, 0xffff0000, v118
	v_pk_mul_f32 v[120:121], v[124:125], v[120:121]
	v_lshl_add_u64 v[124:125], s[52:53], 0, v[140:141]
	v_cvt_pk_bf16_f32 v118, v120, v121
	v_lshlrev_b32_e32 v120, 16, v119
	v_and_b32_e32 v121, 0xffff0000, v119
	v_pk_mul_f32 v[120:121], v[126:127], v[120:121]
	v_pk_add_f32 v[126:127], v[130:131], v[108:109] op_sel_hi:[1,0]
	v_cvt_pk_bf16_f32 v119, v120, v121
	global_store_dwordx4 v[124:125], v[116:119], off
	s_nop 0
	v_pk_add_f32 v[130:131], v[134:135], v[108:109] op_sel_hi:[1,0]
	v_pk_add_f32 v[132:133], v[132:133], v[108:109] op_sel_hi:[1,0]
	v_mfma_f32_16x16x32_bf16 v[120:123], v[88:91], v[44:47], v[136:139]
	s_nop 1
	v_mov_b32_e32 v116, v196
	v_mov_b32_e32 v117, v197
	v_mov_b32_e32 v118, v198
	v_mov_b32_e32 v119, v199
	v_lshlrev_b32_e32 v134, 16, v116
	v_and_b32_e32 v135, 0xffff0000, v116
	v_pk_mul_f32 v[128:129], v[128:129], v[134:135]
	v_mfma_f32_16x16x32_bf16 v[104:107], v[80:83], v[44:47], v[104:107]
	v_cvt_pk_bf16_f32 v116, v128, v129
	v_lshlrev_b32_e32 v128, 16, v117
	v_and_b32_e32 v129, 0xffff0000, v117
	v_pk_mul_f32 v[126:127], v[126:127], v[128:129]
	v_mfma_f32_16x16x32_bf16 v[100:103], v[68:71], v[44:47], v[100:103]
	v_cvt_pk_bf16_f32 v117, v126, v127
	v_lshlrev_b32_e32 v126, 16, v118
	v_and_b32_e32 v127, 0xffff0000, v118
	v_pk_mul_f32 v[126:127], v[132:133], v[126:127]
	v_mfma_f32_16x16x32_bf16 v[96:99], v[64:67], v[44:47], v[96:99]
	v_cvt_pk_bf16_f32 v118, v126, v127
	v_lshlrev_b32_e32 v126, 16, v119
	v_and_b32_e32 v127, 0xffff0000, v119
	v_pk_mul_f32 v[126:127], v[130:131], v[126:127]
	v_mfma_f32_16x16x32_bf16 v[88:91], v[88:91], v[60:63], v[92:95]
	v_cvt_pk_bf16_f32 v119, v126, v127
	global_store_dwordx4 v[124:125], v[116:119], off offset:64
	s_nop 0
	v_mfma_f32_16x16x32_bf16 v[80:83], v[80:83], v[60:63], v[84:87]
	v_add_u32_e32 v116, 32, v112
	v_ashrrev_i32_e32 v117, 31, v116
	v_lshlrev_b64 v[124:125], 12, v[116:117]
	v_or_b32_e32 v124, v124, v115
	v_lshl_add_u64 v[126:127], s[26:27], 0, v[124:125]
	s_nop 0
; __device__ __forceinline__ unsigned pk2(float lo, float hi) { return cvt_pk_bf16(lo, hi); }
; __device__ __forceinline__ void unit(const Frame& F, int c, int g, const bf16x8 (&af)[4][4]) {
;     ...
;     for (int m = 0; m < 4; ++m) {
;         const int p = wr * 64 + m * 16 + fr; const float bsp = F.b_sp[g * 128 + p];
;         const size_t rowoff = (size_t)(tok0 + p) * EA + ch0 + wc * 64 + 8 * fq;
; #pragma unroll
;         for (int h2 = 0; h2 < 2; ++h2) {
;             const u32x4 uu = *(const u32x4*)(F.U + rowoff + h2 * 32);
;             const f32x4 s0 = acc[m][2 * h2] + bsp, s1 = acc[m][2 * h2 + 1] + bsp;
;             u32x4 o;
;             o.x = pk2(bflo(uu.x) * s0[0], bfhi(uu.x) * s0[1]); o.y = pk2(bflo(uu.y) * s0[2], bfhi(uu.y) * s0[3]);
;             o.z = pk2(bflo(uu.z) * s1[0], bfhi(uu.z) * s1[1]); o.w = pk2(bflo(uu.w) * s1[2], bfhi(uu.w) * s1[3]);
;             *(u32x4*)(F.ABUF + rowoff + h2 * 32) = o;
;         }
;     }
;     __syncthreads();
	v_lshl_add_u64 v[124:125], s[52:53], 0, v[124:125]
	v_add_u32_e32 v112, 48, v112
	v_ashrrev_i32_e32 v113, 31, v112
	v_lshlrev_b64 v[112:113], 12, v[112:113]
	v_or_b32_e32 v112, v112, v115
	v_mfma_f32_16x16x32_bf16 v[68:71], v[68:71], v[60:63], v[76:79]
	s_nop 1
	v_mov_b32_e32 v108, v218
	v_pk_add_f32 v[122:123], v[122:123], v[108:109] op_sel_hi:[1,0]
	v_pk_add_f32 v[120:121], v[120:121], v[108:109] op_sel_hi:[1,0]
	v_pk_add_f32 v[106:107], v[106:107], v[108:109] op_sel_hi:[1,0]
	v_pk_add_f32 v[104:105], v[104:105], v[108:109] op_sel_hi:[1,0]
	v_pk_add_f32 v[102:103], v[102:103], v[108:109] op_sel_hi:[1,0]
	v_pk_add_f32 v[100:101], v[100:101], v[108:109] op_sel_hi:[1,0]
	v_pk_add_f32 v[98:99], v[98:99], v[108:109] op_sel_hi:[1,0]
	s_nop 1
	v_mov_b32_e32 v116, v200
	v_mov_b32_e32 v117, v201
	v_mov_b32_e32 v118, v202
	v_mov_b32_e32 v119, v203
	v_lshlrev_b32_e32 v128, 16, v116
	v_and_b32_e32 v129, 0xffff0000, v116
	v_lshlrev_b32_e32 v116, 16, v117
	v_and_b32_e32 v117, 0xffff0000, v117
	v_lshlrev_b32_e32 v130, 16, v118
	v_and_b32_e32 v131, 0xffff0000, v118
	v_lshlrev_b32_e32 v118, 16, v119
	v_and_b32_e32 v119, 0xffff0000, v119
	v_pk_mul_f32 v[120:121], v[120:121], v[128:129]
	v_pk_mul_f32 v[116:117], v[122:123], v[116:117]
	v_pk_mul_f32 v[122:123], v[104:105], v[130:131]
	v_pk_mul_f32 v[118:119], v[106:107], v[118:119]
	v_cvt_pk_bf16_f32 v104, v120, v121
	v_cvt_pk_bf16_f32 v105, v116, v117
	v_cvt_pk_bf16_f32 v106, v122, v123
	v_cvt_pk_bf16_f32 v107, v118, v119
	global_store_dwordx4 v[124:125], v[104:107], off
	s_nop 0
	v_pk_add_f32 v[96:97], v[96:97], v[108:109] op_sel_hi:[1,0]
	v_mfma_f32_16x16x32_bf16 v[64:67], v[64:67], v[60:63], v[72:75]
	s_nop 1
	v_mov_b32_e32 v104, v204
	v_mov_b32_e32 v105, v205
	v_mov_b32_e32 v106, v206
	v_mov_b32_e32 v107, v207
	v_lshlrev_b32_e32 v116, 16, v104
	v_and_b32_e32 v117, 0xffff0000, v104
	v_lshlrev_b32_e32 v104, 16, v105
	v_and_b32_e32 v105, 0xffff0000, v105
	v_lshlrev_b32_e32 v118, 16, v106
	v_and_b32_e32 v119, 0xffff0000, v106
	v_lshlrev_b32_e32 v106, 16, v107
	v_and_b32_e32 v107, 0xffff0000, v107
	v_pk_mul_f32 v[100:101], v[100:101], v[116:117]
	v_pk_mul_f32 v[102:103], v[102:103], v[104:105]
	v_pk_mul_f32 v[104:105], v[96:97], v[118:119]
	v_pk_mul_f32 v[106:107], v[98:99], v[106:107]
	v_cvt_pk_bf16_f32 v96, v100, v101
	v_cvt_pk_bf16_f32 v97, v102, v103
	v_cvt_pk_bf16_f32 v98, v104, v105
	v_cvt_pk_bf16_f32 v99, v106, v107
	global_store_dwordx4 v[124:125], v[96:99], off offset:64
	s_nop 0
	v_lshl_add_u64 v[100:101], s[52:53], 0, v[112:113]
	v_lshl_add_u64 v[98:99], s[26:27], 0, v[112:113]
	s_nop 0
	s_nop 1
	v_mov_b32_e32 v96, v219
	v_pk_add_f32 v[84:85], v[90:91], v[96:97] op_sel_hi:[1,0]
	v_pk_add_f32 v[86:87], v[88:89], v[96:97] op_sel_hi:[1,0]
	v_pk_add_f32 v[82:83], v[82:83], v[96:97] op_sel_hi:[1,0]
	v_pk_add_f32 v[80:81], v[80:81], v[96:97] op_sel_hi:[1,0]
	s_nop 1
	v_mov_b32_e32 v92, v208
	v_mov_b32_e32 v93, v209
	v_mov_b32_e32 v94, v210
	v_mov_b32_e32 v95, v211
	v_lshlrev_b32_e32 v88, 16, v92
	v_and_b32_e32 v89, 0xffff0000, v92
	v_lshlrev_b32_e32 v90, 16, v93
	v_and_b32_e32 v91, 0xffff0000, v93
	v_lshlrev_b32_e32 v92, 16, v94
	v_and_b32_e32 v93, 0xffff0000, v94
	v_lshlrev_b32_e32 v94, 16, v95
	v_and_b32_e32 v95, 0xffff0000, v95
	v_pk_mul_f32 v[86:87], v[86:87], v[88:89]
	v_pk_mul_f32 v[84:85], v[84:85], v[90:91]
	v_pk_mul_f32 v[88:89], v[80:81], v[92:93]
	v_pk_mul_f32 v[90:91], v[82:83], v[94:95]
	v_cvt_pk_bf16_f32 v80, v86, v87
	v_cvt_pk_bf16_f32 v81, v84, v85
	v_cvt_pk_bf16_f32 v82, v88, v89
	v_cvt_pk_bf16_f32 v83, v90, v91
	global_store_dwordx4 v[100:101], v[80:83], off
	s_nop 0
	v_pk_add_f32 v[70:71], v[70:71], v[96:97] op_sel_hi:[1,0]
	v_pk_add_f32 v[68:69], v[68:69], v[96:97] op_sel_hi:[1,0]
	v_pk_add_f32 v[66:67], v[66:67], v[96:97] op_sel_hi:[1,0]
	v_pk_add_f32 v[64:65], v[64:65], v[96:97] op_sel_hi:[1,0]
	s_nop 1
	v_mov_b32_e32 v80, v212
	v_mov_b32_e32 v81, v213
	v_mov_b32_e32 v82, v214
	v_mov_b32_e32 v83, v215
	v_lshlrev_b32_e32 v72, 16, v80
	v_and_b32_e32 v73, 0xffff0000, v80
	v_lshlrev_b32_e32 v74, 16, v81
	v_and_b32_e32 v75, 0xffff0000, v81
	v_lshlrev_b32_e32 v76, 16, v82
	v_and_b32_e32 v77, 0xffff0000, v82
	v_lshlrev_b32_e32 v78, 16, v83
	v_and_b32_e32 v79, 0xffff0000, v83
	v_pk_mul_f32 v[68:69], v[68:69], v[72:73]
	v_pk_mul_f32 v[70:71], v[70:71], v[74:75]
	v_pk_mul_f32 v[72:73], v[64:65], v[76:77]
	v_pk_mul_f32 v[74:75], v[66:67], v[78:79]
	v_cvt_pk_bf16_f32 v64, v68, v69
	v_cvt_pk_bf16_f32 v65, v70, v71
	v_cvt_pk_bf16_f32 v66, v72, v73
	v_cvt_pk_bf16_f32 v67, v74, v75
	global_store_dwordx4 v[100:101], v[64:67], off offset:64
	s_barrier
	s_cbranch_scc0 .LBB0_310
